# in-proj K-loop LDS-DMA pieces use scalar base + immediate offsets (one m0 write per operand, no per-piece 64-bit VALU address math)
# speedup vs baseline: 1.1085x; 1.0057x over previous
; #define RAW_BARRIER() do { asm volatile("s_waitcnt lgkmcnt(0)" ::: "memory"); __builtin_amdgcn_s_barrier(); } while (0)
; #define GEMM_READ2(A_, B_, FA, FB) asm volatile( \
;         "ds_read_b128 %0, %4\n\tds_read_b128 %1, %4 offset:2048\n\tds_read_b128 %2, %5\n\tds_read_b128 %3, %5 offset:2048" \
;         : "=&v"(FA[0]), "=&v"(FA[1]), "=&v"(FB[0]), "=&v"(FB[1]) : "v"(A_), "v"(B_) : "memory")
; template <int WM, class Epi>
; DI void gemm_mfma(const bf16_t* __restrict__ A, const bf16_t* __restrict__ Bt, int Arows, int Brows, int MT, int NT, unsigned char* smem, int bid, int nb, int wave, Epi epi) {
;     ...
;     auto issue = [&](int kt, int buf) {
; #pragma unroll
;       for (int i = 0; i < NAW; ++i)
;         __builtin_amdgcn_global_load_lds((const unsigned*)(abase + kt * astep + i * 1024 + voff),
;                                          (__attribute__((address_space(3))) unsigned*)(smem + buf * STAGE + (wvu * NAW + i) * 1024), 16, 0, 0);
; #pragma unroll
;       for (int i = 0; i < 2; ++i)
;         __builtin_amdgcn_global_load_lds((const unsigned*)(bbase + kt * bstep + i * 1024 + voff),
;                                          (__attribute__((address_space(3))) unsigned*)(smem + buf * STAGE + A_BYTES + (wvu * 2 + i) * 1024), 16, 0, 0);
;     };
;     ...
; #pragma unroll 1
;     for (int kt = 0; kt < NKT; ++kt) {
;       const int ahead = (NKT - 1 - kt < NST - 2) ? (NKT - 1 - kt) : (NST - 2);
;       if (NI == 4) { if (ahead == 2) asm volatile("s_waitcnt vmcnt(8)" ::: "memory"); else if (ahead == 1) asm volatile("s_waitcnt vmcnt(4)" ::: "memory"); else asm volatile("s_waitcnt vmcnt(0)" ::: "memory"); }
;       else { if (ahead == 1) asm volatile("s_waitcnt vmcnt(6)" ::: "memory"); else asm volatile("s_waitcnt vmcnt(0)" ::: "memory"); }
;       RAW_BARRIER();
;       if (kt + NST - 1 < NKT) issue(kt + NST - 1, (kt + NST - 1) % NST);
;       const unsigned sb = lds0 + (unsigned)((kt % NST) * STAGE);
;       const unsigned a0 = sb + offA0, a1 = sb + offA1, b0 = sb + offB0, b1 = sb + offB1;
;       if constexpr (WM == 4) GEMM_READ4(a0, b0, fa0, fb0); else GEMM_READ2(a0, b0, fa0, fb0);
;       GEMM_MMA(fa1, fb1);
;       if constexpr (WM == 4) { GEMM_WAIT4(fa0, fb0); GEMM_READ4(a1, b1, fa1, fb1); } else { GEMM_WAIT2(fa0, fb0); GEMM_READ2(a1, b1, fa1, fb1); }
;       GEMM_MMA(fa0, fb0);
;     }
.LBB0_169:
	s_waitcnt lgkmcnt(0)
	s_add_i32 s6, s21, -2
	s_cmp_gt_u32 s6, 29
	s_barrier
	s_cbranch_scc1 .LBB0_164
	s_mul_i32 s7, s21, 0xab
	s_bfe_u32 s7, s7, 0x70009
	s_mul_i32 s7, s7, 3
	s_sub_i32 s7, s21, s7
	s_and_b32 s7, s7, 0xff
	s_mulk_i32 s7, 0x6000
	s_add_i32 s25, s7, s9
	s_add_i32 s7, s7, s20
	s_mul_i32 s26, s6, 0xab
	s_bfe_u32 s26, s26, 0x70009
	s_mul_i32 s26, s26, 3
	s_sub_i32 s6, s6, s26
	s_and_b32 s6, s6, 0xff
	s_mulk_i32 s6, 0x6000
	v_add_u32_e32 v160, s6, v159
	v_add_u32_e32 v170, s6, v165
	ds_read_b128 v[196:199], v160
	ds_read_b128 v[200:203], v160 offset:2048
	ds_read_b128 v[204:207], v160 offset:4096
	ds_read_b128 v[208:211], v160 offset:6144
	ds_read_b128 v[212:215], v170
	ds_read_b128 v[216:219], v170 offset:2048
	s_add_u32 s98, s0, 0x8c000
	s_addc_u32 s99, s1, 0
	s_add_u32 s100, s4, 0x2006000
	s_addc_u32 s101, s5, 0
	s_add_i32 m0, s7, 0x4000
	s_setprio 1
	v_mfma_f32_32x32x16_bf16 v[112:127], v[148:151], v[144:147], v[112:127]
	global_load_lds_dwordx4 v154, s[98:99]
	v_add_u32_e32 v160, s6, v164
	v_add_u32_e32 v170, s6, v166
	v_mfma_f32_32x32x16_bf16 v[96:111], v[148:151], v[136:139], v[96:111]
	v_mfma_f32_32x32x16_bf16 v[80:95], v[140:143], v[144:147], v[80:95]
	global_load_lds_dwordx4 v154, s[98:99] offset:1024
	s_mov_b32 m0, s25
	v_mfma_f32_32x32x16_bf16 v[64:79], v[140:143], v[136:139], v[64:79]
	v_mfma_f32_32x32x16_bf16 v[48:63], v[132:135], v[144:147], v[48:63]
	global_load_lds_dwordx4 v154, s[100:101]
	v_mfma_f32_32x32x16_bf16 v[32:47], v[132:135], v[136:139], v[32:47]
	v_mfma_f32_32x32x16_bf16 v[16:31], v[128:131], v[144:147], v[16:31]
	global_load_lds_dwordx4 v154, s[100:101] offset:1024
	v_mfma_f32_32x32x16_bf16 v[0:15], v[128:131], v[136:139], v[0:15]
	s_setprio 0
	s_waitcnt lgkmcnt(0)
	ds_read_b128 v[148:151], v160
	ds_read_b128 v[140:143], v160 offset:2048
	ds_read_b128 v[132:135], v160 offset:4096
	ds_read_b128 v[128:131], v160 offset:6144
	ds_read_b128 v[144:147], v170
	ds_read_b128 v[136:139], v170 offset:2048
	s_setprio 1
	v_mfma_f32_32x32x16_bf16 v[112:127], v[196:199], v[212:215], v[112:127]
	global_load_lds_dwordx4 v154, s[100:101] offset:2048
	v_mfma_f32_32x32x16_bf16 v[96:111], v[196:199], v[216:219], v[96:111]
	v_mfma_f32_32x32x16_bf16 v[80:95], v[200:203], v[212:215], v[80:95]
	global_load_lds_dwordx4 v154, s[100:101] offset:3072
	v_mfma_f32_32x32x16_bf16 v[64:79], v[200:203], v[216:219], v[64:79]
	v_mfma_f32_32x32x16_bf16 v[48:63], v[204:207], v[212:215], v[48:63]
	v_mfma_f32_32x32x16_bf16 v[32:47], v[204:207], v[216:219], v[32:47]
	v_mfma_f32_32x32x16_bf16 v[16:31], v[208:211], v[212:215], v[16:31]
	v_mfma_f32_32x32x16_bf16 v[0:15], v[208:211], v[216:219], v[0:15]
	s_setprio 0
	s_add_u32 s0, s0, 0x46000
	s_addc_u32 s1, s1, 0
	s_add_u32 s4, s4, 0x120000
	s_addc_u32 s5, s5, 0
	s_add_i32 s21, s21, 1
	s_branch .LBB0_165
